# attention branch B: q loads issued before next-unit K/V prefetch, rpb scale deferred to commit, counted vmcnt so prefetch overlaps compute
# speedup vs baseline: 1.0151x; 1.0151x over previous
; __device__ __forceinline__ void attn_b_prefetch(const bf16* Z, const float* rpb, int unit, v4u (&kr)[9], v4u (&vr)[9], float (&tr)[2]) {
;     ...
;     for (int k = 0; k < 2; ++k) { const int it = tid + k * NTHREADS, e = it - 16, dr = e >> 5, dc = e & 31;
;         tr[k] = (it >= B_TREAL) ? -INFINITY : ((e >= 0 && dr < 15 && dc < 31) ? rpb[h * 465 + dr * 31 + dc] * LOG2E : 0.f); }
.LBB0_274:
	s_movk_i32 s1, 0x21f
	v_add_u32_e32 v58, -16, v218
	v_cmp_lt_u32_e32 vcc, s1, v218
	s_movk_i32 s1, 0x220
	v_lshrrev_b32_e32 v78, 3, v218
	v_and_b32_e32 v60, 31, v218
	v_bitop3_b32 v59, v218, 16, 31 bitop3:0x6c
	v_ashrrev_i32_e32 v61, 5, v58
	v_cmp_gt_u32_e64 s[4:5], s1, v218
	v_mov_b32_e32 v58, 0xff800000
	v_mov_b32_e32 v141, 0xff800000
	s_and_saveexec_b64 s[10:11], s[4:5]
	s_cbranch_execz .LBB0_278
	v_cmp_gt_i32_e64 s[6:7], 15, v61
	v_cmp_ne_u32_e64 s[8:9], 15, v60
	v_cmp_lt_u32_e64 s[4:5], 15, v218
	s_and_b64 s[6:7], s[8:9], s[6:7]
	s_and_b64 s[6:7], s[4:5], s[6:7]
	v_mov_b32_e32 v141, 0
	s_and_saveexec_b64 s[4:5], s[6:7]
	s_cbranch_execz .LBB0_277
	s_mulk_i32 s0, 0x1d1
	v_mul_i32_i24_e32 v79, 31, v61
	v_add3_u32 v80, v79, v59, s0
	v_ashrrev_i32_e32 v81, 31, v80
	v_lshl_add_u64 v[80:81], v[80:81], 2, s[46:47]
	global_load_dword v141, v[80:81], off

; __global__ void __launch_bounds__(NTHREADS, 2) mk_fwd(Args args) {
;     ...
;             v4u kr[9], vr[9]; float tr[2]; int u = vcu; const int NU = BATCH * 8 * 64;
;             if (u < NU) attn_b_prefetch(Zb, rpb, u, kr, vr, tr);
;             for (; u < NU; u += G) {
;                 attn_b_commit(lds, kr, vr, tr);
;                 __syncthreads();
;                 if (u + G < NU) attn_b_prefetch(Zb, rpb, u + G, kr, vr, tr);
;                 asm volatile("" ::: "memory");
;                 attn_b_unit(lds, Zb, YA, u);
;                 __syncthreads();
.Lb_nonext:
	s_waitcnt vmcnt(0)
	s_branch .LBB0_280

; #define LAS __attribute__((address_space(3)))
; __device__ __forceinline__ size_t tmo(int row, int ct, int nct) { return ((size_t)(row >> 8) * nct + ct) * 32768 + (size_t)(row & 255) * 128; }
; __device__ __forceinline__ void attn_b_unit(LAS unsigned char* lds, const bf16* Z, bf16* Y, int unit) {
;     ...
;     const size_t qtok = tok0 + (size_t)rq * 64 + c;
;     const unsigned char* qp = (const unsigned char*)Z + tmo((int)qtok, Z_QB / 64 + h, ZLD / 64) + 16 * g;
;     const bf16x8 qf0 = *(const bf16x8*)qp, qf1 = *(const bf16x8*)(qp + 64);
;     float m0 = -1e30f, l0 = 0.f, m1 = -1e30f, l1 = 0.f;
;     f32x4 O0[4], O1[4];
; #pragma unroll
;     for (int d = 0; d < 4; ++d) { O0[d] = (f32x4){0.f, 0.f, 0.f, 0.f}; O1[d] = (f32x4){0.f, 0.f, 0.f, 0.f}; }
;     const int kcl = kc0 + 4 * g;
;     const int tb = 16 + (kcl - c + 15);
;     const int Rb = (r0q - R0) * 64 + kc0;
;     const LAS unsigned char* kp0 = Kl + swz(Rb + lq, g); const LAS unsigned char* kp1 = Kl + swz(Rb + lq, 4 + g);
;     const LAS unsigned char* vp[4];
;     { const int i = lane & 15, rq4 = i >> 2, p = i & 3;
; #pragma unroll
;       for (int db = 0; db < 4; ++db) vp[db] = Vl + swz(Rb + 4 * g + rq4, 2 * db + (p >> 1)) + 8 * (p & 1); }
;     const LAS float* T0 = T + tb + (r0q - rq + 7) * 32;
;     const LAS float* tpa[4]; const LAS float* tpb[4];
; #pragma unroll
;     for (int r = 0; r < 4; ++r) { const int kca = kcl + r, kcb = kca + 16;
;         tpa[r] = (kca >= cs && kca <= cs + 15) ? T0 + r : T + B_TREAL; tpb[r] = (kcb >= cs && kcb <= cs + 15) ? T0 + 16 + r : T + B_TREAL; }
; #pragma unroll
;     for (int st = 0; st < 4; ++st) {
;         const int offA = st * 8192, offB = offA + 4 * 8192;
;         f32x4 SA0, SA1, SB0, SB1;
;         qk_at(kp0, kp1, offA, qf0, qf1, SA0, SA1);
;         qk_at(kp0, kp1, offB, qf0, qf1, SB0, SB1);
; #pragma unroll
;         for (int r = 0; r < 4; ++r) {
;             SA0[r] += tpa[r][st * 32]; SA1[r] += tpb[r][st * 32]; SB0[r] += tpa[r][st * 32 + 128]; SB1[r] += tpb[r][st * 32 + 128];
;         }
;         softmax_step(SA0, SA1, m0, l0, O0);
;         softmax_step(SB0, SB1, m1, l1, O1);
;         pv_at(vp, offA, SA0, SA1, O0);
;         pv_at(vp, offB, SB0, SB1, O1);
;     }
.LBB0_280:
	s_and_b32 s51, s58, 0x7e
	v_add_u32_e32 v61, s51, v115
	s_and_b32 s26, s59, 0xffffe000
	v_lshlrev_b32_e32 v58, 6, v61
	v_add_u32_e32 v60, s26, v58
	s_bfe_u32 s50, s72, 0x30006
	v_ashrrev_i32_e32 v60, 8, v60
	s_add_i32 s26, s50, 12
	v_or_b32_e32 v58, v58, v116
	v_lshlrev_b32_e32 v58, 7, v58
	v_and_b32_e32 v58, 0x7f80, v58
	v_sub_co_u32_e64 v86, s[58:59], s51, 4
	v_subrev_co_u32_e32 v87, vcc, 4, v61
	v_min_u32_e32 v86, 0x78, v86
	v_min_u32_e32 v87, 0x78, v87
	v_cndmask_b32_e64 v86, v86, 0, s[58:59]
	v_cndmask_b32_e64 v87, v87, 0, vcc
	v_sub_u32_e32 v86, v87, v86
	v_lshl_or_b32 v86, v86, 6, v117
	v_sub_u32_e32 v61, v87, v61
	v_add_u32_e32 v87, v86, v113
	v_add_u32_e32 v90, v86, v119
	v_bitop3_b32 v86, v87, v114, 7 bitop3:0x6c
	v_lshlrev_b32_e32 v145, 7, v87
	v_lshlrev_b32_e32 v86, 4, v86
	v_lshl_add_u32 v61, v61, 7, v121
	v_add3_u32 v154, 0, v86, v145
	v_mov_b32_e32 v142, s53
	v_add_u32_e32 v91, 0x3fc, v61
	v_add_u32_e32 v92, 0x43c, v61
	v_bitop3_b32 v143, v87, v118, 7 bitop3:0x6c
	ds_read_b128 v[86:89], v154
	v_lshl_add_u32 v168, v90, 7, v120
	v_bitop3_b32 v144, v90, v134, 7 bitop3:0x6c
	v_bitop3_b32 v164, v90, v135, 7 bitop3:0x6c
	v_bitop3_b32 v165, v90, v136, 7 bitop3:0x6c
	v_bitop3_b32 v169, v90, v137, 7 bitop3:0x6c
	v_cndmask_b32_e64 v153, v91, v142, s[6:7]
	v_cndmask_b32_e64 v152, v92, v142, s[8:9]
	ds_read_b128 v[90:93], v154 offset:2048
	v_lshlrev_b32_e32 v143, 4, v143
	v_add3_u32 v155, 0, v143, v145
	v_add_u32_e32 v94, 0x400, v61
	v_add_u32_e32 v95, 0x440, v61
	v_add_u32_e32 v96, 0x404, v61
	v_add_u32_e32 v98, 0x444, v61
	v_add_u32_e32 v99, 0x408, v61
	ds_read_b128 v[156:159], v155
	v_cndmask_b32_e64 v151, v94, v142, s[10:11]
	v_cndmask_b32_e64 v149, v95, v142, s[12:13]
	v_cndmask_b32_e64 v147, v96, v142, s[14:15]
	ds_read_b128 v[94:97], v154 offset:32768
	v_cndmask_b32_e64 v148, v98, v142, s[16:17]
	v_cndmask_b32_e64 v146, v99, v142, s[18:19]
	ds_read_b128 v[98:101], v154 offset:34816
	ds_read_b128 v[160:163], v155 offset:2048
	v_lshl_add_u32 v145, v144, 4, v168
	v_lshl_add_u32 v144, v164, 4, v168
	v_lshl_add_u32 v143, v165, 4, v168
	ds_read_b128 v[164:167], v155 offset:32768
	v_add_u32_e32 v61, 0x448, v61
	v_cndmask_b32_e64 v150, v61, v142, s[20:21]
	v_lshl_add_u32 v142, v169, 4, v168
	s_lshl_b32 s26, s50, 15
	s_mov_b32 s58, s57
	s_mov_b32 s59, s56
	s_mov_b32 s72, s55
	s_waitcnt vmcnt(14) lgkmcnt(6)
	v_mfma_f32_16x16x32_bf16 v[86:89], v[86:89], v[82:85], 0
	s_waitcnt lgkmcnt(5)
	v_mfma_f32_16x16x32_bf16 v[90:93], v[90:93], v[82:85], 0
	s_waitcnt lgkmcnt(4)
	v_mfma_f32_16x16x32_bf16 v[86:89], v[156:159], v[78:81], v[86:89]
	ds_read2st64_b32 v[168:169], v153 offset1:2
	ds_read_b128 v[156:159], v155 offset:34816
	s_waitcnt lgkmcnt(5)
	v_mfma_f32_16x16x32_bf16 v[94:97], v[94:97], v[82:85], 0
	s_waitcnt lgkmcnt(1)
	s_nop 2
	v_add_f32_e32 v61, v86, v168
	v_mfma_f32_16x16x32_bf16 v[98:101], v[98:101], v[82:85], 0
	v_mfma_f32_16x16x32_bf16 v[90:93], v[160:163], v[78:81], v[90:93]
	ds_read2st64_b32 v[160:161], v152 offset1:2
	ds_read2st64_b32 v[162:163], v151 offset1:2
	ds_read2st64_b32 v[170:171], v149 offset1:2
	v_mfma_f32_16x16x32_bf16 v[94:97], v[164:167], v[78:81], v[94:97]
	ds_read2st64_b32 v[164:165], v147 offset1:2
	ds_read2st64_b32 v[166:167], v148 offset1:2
	ds_read2st64_b32 v[172:173], v146 offset1:2
	s_waitcnt lgkmcnt(5)
	v_add_f32_e32 v90, v90, v160
	s_waitcnt lgkmcnt(3)
	v_add_f32_e32 v91, v91, v170
	v_mfma_f32_16x16x32_bf16 v[98:101], v[156:159], v[78:81], v[98:101]
	v_add_f32_e32 v156, v87, v162
	ds_read2st64_b32 v[86:87], v150 offset1:2
	s_waitcnt lgkmcnt(2)
	v_add_f32_e32 v92, v92, v166
	v_add_f32_e32 v88, v88, v164
	v_add_f32_e32 v157, v96, v165
	s_waitcnt lgkmcnt(1)
	v_add_f32_e32 v89, v89, v172
	s_waitcnt lgkmcnt(0)
	v_add_f32_e32 v86, v93, v86
	v_max_f32_e32 v96, v92, v86
	v_add_f32_e32 v160, v101, v87
	v_max_f32_e32 v87, v61, v156
	v_max_f32_e32 v93, v88, v89
	v_max3_f32 v96, v90, v91, v96
	v_max3_f32 v87, v87, v93, v96
	v_mov_b32_e32 v93, v87
	s_nop 1
	v_permlane16_swap_b32_e32 v87, v93
	v_max_f32_e32 v93, v93, v93
	v_max_f32_e32 v87, v87, v87
	v_max_f32_e32 v87, v87, v93
	v_mov_b32_e32 v93, v87
	s_nop 1
	v_permlane32_swap_b32_e32 v87, v93
	v_max3_f32 v196, v87, v93, s54
	v_sub_f32_e32 v61, v61, v196
	v_exp_f32_e32 v188, v61
	v_sub_f32_e32 v61, v90, v196
	v_exp_f32_e32 v189, v61
	v_sub_f32_e32 v61, v156, v196
	v_exp_f32_e32 v190, v61
	v_sub_f32_e32 v61, v91, v196
	v_exp_f32_e32 v191, v61
	v_sub_f32_e32 v61, v88, v196
	v_exp_f32_e32 v192, v61
	v_sub_f32_e32 v61, v92, v196
	v_add_f32_e32 v158, v100, v167
	v_exp_f32_e32 v193, v61
	v_sub_f32_e32 v61, v89, v196
	v_add_f32_e32 v94, v94, v169
	v_add_f32_e32 v98, v98, v161
	v_add_f32_e32 v95, v95, v163
	v_add_f32_e32 v99, v99, v171
	v_add_f32_e32 v159, v97, v173
	v_exp_f32_e32 v195, v61
	v_sub_f32_e32 v61, v86, v196
	v_max_f32_e32 v91, v158, v160
	v_exp_f32_e32 v197, v61
	v_max_f32_e32 v61, v94, v95
	v_max_f32_e32 v90, v157, v159
	v_max3_f32 v91, v98, v99, v91
	v_max3_f32 v61, v61, v90, v91
	v_mov_b32_e32 v90, v61
	s_nop 1
	v_permlane16_swap_b32_e32 v61, v90
	v_max_f32_e32 v90, v90, v90
	v_max_f32_e32 v61, v61, v61
	v_max_f32_e32 v61, v61, v90
	v_mov_b32_e32 v90, v61
	s_nop 1
	v_permlane32_swap_b32_e32 v61, v90
	v_max3_f32 v198, v61, v90, s54
	v_sub_f32_e32 v90, v94, v198
	v_exp_f32_e32 v199, v90
	v_sub_f32_e32 v90, v98, v198
	v_sub_f32_e32 v87, 0xf149f2ca, v196
	v_exp_f32_e32 v200, v90
	v_sub_f32_e32 v90, v95, v198
	v_exp_f32_e32 v194, v87
	v_exp_f32_e32 v201, v90
	v_sub_f32_e32 v90, v99, v198
	v_exp_f32_e32 v202, v90
	v_cvt_pk_bf16_f32 v90, v188, v190
	v_cvt_pk_bf16_f32 v91, v192, v195
	v_cvt_pk_bf16_f32 v92, v189, v191
	v_cvt_pk_bf16_f32 v93, v193, v197
	ds_read_b64_tr_b16 v[94:95], v145
	ds_read_b64_tr_b16 v[96:97], v145 offset:2048
	v_sub_f32_e32 v98, v157, v198
	v_exp_f32_e32 v203, v98
	ds_read_b64_tr_b16 v[98:99], v144
	ds_read_b64_tr_b16 v[100:101], v144 offset:2048
	v_mul_f32_e32 v86, 0, v194
	v_sub_f32_e32 v156, v158, v198
	v_mov_b32_e32 v87, v86
	v_mov_b32_e32 v88, v86
	v_mov_b32_e32 v89, v86
	v_sub_f32_e32 v61, 0xf149f2ca, v198
	v_exp_f32_e32 v204, v156
	v_sub_f32_e32 v156, v159, v198
	v_exp_f32_e32 v205, v156
	s_waitcnt lgkmcnt(2)
; __device__ __forceinline__ void attn_b_unit(LAS unsigned char* lds, const bf16* Z, bf16* Y, int unit) {
;     ...
;     for (int st = 0; st < 4; ++st) {
;         const int offA = st * 8192, offB = offA + 4 * 8192;
;         f32x4 SA0, SA1, SB0, SB1;
;         qk_at(kp0, kp1, offA, qf0, qf1, SA0, SA1);
;         qk_at(kp0, kp1, offB, qf0, qf1, SB0, SB1);
; #pragma unroll
;         for (int r = 0; r < 4; ++r) {
;             SA0[r] += tpa[r][st * 32]; SA1[r] += tpb[r][st * 32]; SB0[r] += tpa[r][st * 32 + 128]; SB1[r] += tpb[r][st * 32 + 128];
;         }
;         softmax_step(SA0, SA1, m0, l0, O0);
;         softmax_step(SB0, SB1, m1, l1, O1);
;         pv_at(vp, offA, SA0, SA1, O0);
;         pv_at(vp, offB, SB0, SB1, O1);
;     }
	v_mfma_f32_16x16x32_bf16 v[156:159], v[94:97], v[90:93], v[86:89]
	v_sub_f32_e32 v94, v160, v198
	v_exp_f32_e32 v207, v61
	v_exp_f32_e32 v206, v94
	s_waitcnt lgkmcnt(0)
	v_mfma_f32_16x16x32_bf16 v[160:163], v[98:101], v[90:93], v[86:89]
	ds_read_b64_tr_b16 v[94:95], v143
	ds_read_b64_tr_b16 v[96:97], v143 offset:2048
	ds_read_b64_tr_b16 v[98:99], v142
	ds_read_b64_tr_b16 v[100:101], v142 offset:2048
	v_cvt_pk_bf16_f32 v164, v199, v201
	v_cvt_pk_bf16_f32 v165, v203, v205
	v_cvt_pk_bf16_f32 v166, v200, v202
	v_cvt_pk_bf16_f32 v167, v204, v206
	ds_read_b64_tr_b16 v[168:169], v145 offset:32768
	ds_read_b64_tr_b16 v[170:171], v145 offset:34816
	v_mul_f32_e32 v176, 0, v207
	v_mov_b32_e32 v177, v176
	v_mov_b32_e32 v178, v176
	v_mov_b32_e32 v179, v176
	s_waitcnt lgkmcnt(4)
	v_mfma_f32_16x16x32_bf16 v[172:175], v[94:97], v[90:93], v[86:89]
	ds_read_b64_tr_b16 v[94:95], v144 offset:32768
	ds_read_b64_tr_b16 v[96:97], v144 offset:34816
	v_add_f32_e32 v188, v188, v190
	v_add_f32_e32 v199, v199, v201
	s_waitcnt lgkmcnt(4)
	v_mfma_f32_16x16x32_bf16 v[180:183], v[98:101], v[90:93], v[86:89]
	s_nop 2
	ds_read_b64_tr_b16 v[86:87], v143 offset:32768
	ds_read_b64_tr_b16 v[88:89], v143 offset:34816
	v_add_f32_e32 v200, v200, v202
	v_add_f32_e32 v201, v204, v206
	s_waitcnt lgkmcnt(4)
	v_mfma_f32_16x16x32_bf16 v[98:101], v[168:171], v[164:167], v[176:179]
	ds_read_b64_tr_b16 v[168:169], v142 offset:32768
	ds_read_b64_tr_b16 v[170:171], v142 offset:34816
	ds_read_b128 v[184:187], v154 offset:8192
	v_ashrrev_i32_e32 v61, 31, v60
	s_waitcnt lgkmcnt(5)
	v_mfma_f32_16x16x32_bf16 v[94:97], v[94:97], v[164:167], v[176:179]
	v_lshlrev_b64 v[60:61], 19, v[60:61]
	v_lshl_add_u64 v[60:61], s[40:41], 0, v[60:61]
	v_lshl_add_u64 v[60:61], v[60:61], 0, s[26:27]
	s_waitcnt lgkmcnt(3)
	v_mfma_f32_16x16x32_bf16 v[90:93], v[86:89], v[164:167], v[176:179]
	v_lshl_add_u64 v[60:61], v[60:61], 0, v[58:59]
	s_waitcnt lgkmcnt(1)
	v_mfma_f32_16x16x32_bf16 v[86:89], v[168:171], v[164:167], v[176:179]
	ds_read_b128 v[164:167], v155 offset:8192
	ds_read_b128 v[168:171], v154 offset:10240
	s_waitcnt lgkmcnt(2)
	v_mfma_f32_16x16x32_bf16 v[176:179], v[184:187], v[82:85], 0
	ds_read_b128 v[184:187], v155 offset:10240
	s_waitcnt lgkmcnt(1)
	v_mfma_f32_16x16x32_bf16 v[168:171], v[168:171], v[82:85], 0
	v_mfma_f32_16x16x32_bf16 v[164:167], v[164:167], v[78:81], v[176:179]
	s_nop 3
	v_add_f32_e32 v176, v192, v195
	v_add_f32_e32 v192, v188, v176
	ds_read_b128 v[176:179], v154 offset:40960
	v_fmac_f32_e32 v192, 0, v194
	v_add_f32_e32 v194, v189, v191
	s_waitcnt lgkmcnt(1)
	v_mfma_f32_16x16x32_bf16 v[168:171], v[184:187], v[78:81], v[168:171]
	v_add_f32_e32 v184, v193, v197
	v_add_f32_e32 v193, v194, v184
	ds_read_b128 v[184:187], v154 offset:43008
	ds_read_b128 v[188:191], v155 offset:40960
	v_add_f32_e32 v197, v193, v192
	ds_read_b128 v[192:195], v155 offset:43008
	s_waitcnt lgkmcnt(3)
	v_mfma_f32_16x16x32_bf16 v[176:179], v[176:179], v[82:85], 0
	s_waitcnt lgkmcnt(2)
	v_mfma_f32_16x16x32_bf16 v[184:187], v[184:187], v[82:85], 0
	s_waitcnt lgkmcnt(1)
	v_mfma_f32_16x16x32_bf16 v[176:179], v[188:191], v[78:81], v[176:179]
	v_add_f32_e32 v188, v203, v205
	v_add_f32_e32 v199, v199, v188
	ds_read2_b32 v[188:189], v153 offset0:32 offset1:160
	ds_read2_b32 v[190:191], v152 offset0:32 offset1:160
	s_waitcnt lgkmcnt(2)
	v_mfma_f32_16x16x32_bf16 v[184:187], v[192:195], v[78:81], v[184:187]
	ds_read2_b32 v[192:193], v151 offset0:32 offset1:160
	ds_read2_b32 v[194:195], v149 offset0:32 offset1:160
	s_waitcnt lgkmcnt(3)
	v_add_f32_e32 v188, v164, v188
	s_waitcnt lgkmcnt(2)
	v_add_f32_e32 v190, v168, v190
	v_add_f32_e32 v189, v176, v189
	s_nop 0
	v_add_f32_e32 v191, v184, v191
	s_waitcnt lgkmcnt(1)
	v_add_f32_e32 v192, v165, v192
	ds_read2_b32 v[164:165], v147 offset0:32 offset1:160
	s_waitcnt lgkmcnt(1)
	v_add_f32_e32 v194, v169, v194
	v_add_f32_e32 v193, v177, v193
	ds_read2_b32 v[168:169], v148 offset0:32 offset1:160
	v_add_f32_e32 v195, v185, v195
	ds_read2_b32 v[176:177], v146 offset0:32 offset1:160
	ds_read2_b32 v[184:185], v150 offset0:32 offset1:160
	s_waitcnt lgkmcnt(3)
	v_add_f32_e32 v164, v166, v164
	v_add_f32_e32 v178, v178, v165
	s_waitcnt lgkmcnt(2)
	v_add_f32_e32 v166, v170, v168
	s_waitcnt lgkmcnt(1)
	v_add_f32_e32 v165, v167, v176
	s_waitcnt lgkmcnt(0)
; __device__ __forceinline__ void attn_b_unit(LAS unsigned char* lds, const bf16* Z, bf16* Y, int unit) {
;     ...
;     for (int st = 0; st < 4; ++st) {
;         const int offA = st * 8192, offB = offA + 4 * 8192;
;         f32x4 SA0, SA1, SB0, SB1;
;         qk_at(kp0, kp1, offA, qf0, qf1, SA0, SA1);
;         qk_at(kp0, kp1, offB, qf0, qf1, SB0, SB1);
; #pragma unroll
;         for (int r = 0; r < 4; ++r) {
;             SA0[r] += tpa[r][st * 32]; SA1[r] += tpb[r][st * 32]; SB0[r] += tpa[r][st * 32 + 128]; SB1[r] += tpb[r][st * 32 + 128];
;         }
;         softmax_step(SA0, SA1, m0, l0, O0);
;         softmax_step(SB0, SB1, m1, l1, O1);
;         pv_at(vp, offA, SA0, SA1, O0);
;         pv_at(vp, offB, SB0, SB1, O1);
;     }
	v_add_f32_e32 v167, v171, v184
	v_max_f32_e32 v170, v166, v167
	v_add_f32_e32 v186, v186, v169
	v_max_f32_e32 v168, v188, v192
	v_max_f32_e32 v169, v164, v165
	v_max3_f32 v170, v190, v194, v170
	v_max3_f32 v168, v168, v169, v170
	v_mov_b32_e32 v169, v168
	s_nop 1
	v_permlane16_swap_b32_e32 v168, v169
	v_max_f32_e32 v169, v169, v169
	v_max_f32_e32 v168, v168, v168
	v_max_f32_e32 v168, v168, v169
	v_mov_b32_e32 v169, v168
	s_nop 1
	v_permlane32_swap_b32_e32 v168, v169
	v_max3_f32 v202, v196, v168, v169
	v_sub_f32_e32 v169, v188, v202
	v_sub_f32_e32 v168, v196, v202
	v_exp_f32_e32 v203, v169
	v_sub_f32_e32 v169, v190, v202
	v_exp_f32_e32 v204, v169
	v_sub_f32_e32 v169, v192, v202
	v_exp_f32_e32 v192, v168
	v_sub_f32_e32 v164, v164, v202
	v_exp_f32_e32 v206, v164
	v_sub_f32_e32 v164, v166, v202
	v_fmac_f32_e32 v199, 0, v207
	v_add_f32_e32 v185, v187, v185
	v_exp_f32_e32 v207, v164
	v_sub_f32_e32 v164, v165, v202
	v_add_f32_e32 v184, v179, v177
	v_exp_f32_e32 v208, v164
	v_sub_f32_e32 v164, v167, v202
	v_pk_mul_f32 v[166:167], v[174:175], v[192:193] op_sel_hi:[1,0]
	v_max_f32_e32 v174, v186, v185
	v_exp_f32_e32 v209, v164
	v_pk_mul_f32 v[164:165], v[172:173], v[192:193] op_sel_hi:[1,0]
	v_max_f32_e32 v172, v189, v193
	v_max_f32_e32 v173, v178, v184
	v_max3_f32 v174, v191, v195, v174
	v_max3_f32 v172, v172, v173, v174
	v_mov_b32_e32 v173, v172
	s_nop 1
	v_permlane16_swap_b32_e32 v172, v173
	v_max_f32_e32 v173, v173, v173
	v_max_f32_e32 v172, v172, v172
	v_max_f32_e32 v172, v172, v173
	v_mov_b32_e32 v173, v172
	s_nop 1
	v_permlane32_swap_b32_e32 v172, v173
	v_max3_f32 v210, v198, v172, v173
	v_sub_f32_e32 v172, v189, v210
	v_sub_f32_e32 v187, v198, v210
	v_exp_f32_e32 v198, v172
	v_sub_f32_e32 v172, v191, v210
	v_exp_f32_e32 v205, v169
	v_sub_f32_e32 v169, v194, v202
	v_exp_f32_e32 v211, v172
	v_sub_f32_e32 v172, v193, v210
	v_exp_f32_e32 v194, v169
	v_pk_mul_f32 v[158:159], v[158:159], v[192:193] op_sel_hi:[1,0]
	v_pk_mul_f32 v[156:157], v[156:157], v[192:193] op_sel_hi:[1,0]
	v_pk_mul_f32 v[162:163], v[162:163], v[192:193] op_sel_hi:[1,0]
	v_pk_mul_f32 v[160:161], v[160:161], v[192:193] op_sel_hi:[1,0]
	v_pk_mul_f32 v[170:171], v[182:183], v[192:193] op_sel_hi:[1,0]
	v_pk_mul_f32 v[168:169], v[180:181], v[192:193] op_sel_hi:[1,0]
	v_exp_f32_e32 v193, v172
	v_sub_f32_e32 v172, v195, v210
	v_exp_f32_e32 v212, v172
	v_sub_f32_e32 v180, v178, v210
	v_cvt_pk_bf16_f32 v172, v203, v205
	v_cvt_pk_bf16_f32 v173, v206, v208
	v_cvt_pk_bf16_f32 v174, v204, v194
	v_cvt_pk_bf16_f32 v175, v207, v209
	ds_read_b64_tr_b16 v[176:177], v145 offset:8192
	ds_read_b64_tr_b16 v[178:179], v145 offset:10240
	v_exp_f32_e32 v195, v180
	ds_read_b64_tr_b16 v[180:181], v144 offset:8192
	ds_read_b64_tr_b16 v[182:183], v144 offset:10240
	s_waitcnt lgkmcnt(2)
	v_mfma_f32_16x16x32_bf16 v[156:159], v[176:179], v[172:175], v[156:159]
	v_sub_f32_e32 v176, v185, v210
	v_exp_f32_e32 v215, v176
	v_sub_f32_e32 v186, v186, v210
	s_waitcnt lgkmcnt(0)
	v_mfma_f32_16x16x32_bf16 v[160:163], v[180:183], v[172:175], v[160:163]
	ds_read_b64_tr_b16 v[176:177], v143 offset:8192
	ds_read_b64_tr_b16 v[178:179], v143 offset:10240
	ds_read_b64_tr_b16 v[180:181], v142 offset:8192
	ds_read_b64_tr_b16 v[182:183], v142 offset:10240
	v_sub_f32_e32 v184, v184, v210
	v_exp_f32_e32 v213, v186
	v_exp_f32_e32 v214, v184
	v_exp_f32_e32 v196, v187
	v_cvt_pk_bf16_f32 v184, v198, v193
	v_cvt_pk_bf16_f32 v185, v195, v214
	v_cvt_pk_bf16_f32 v186, v211, v212
	v_cvt_pk_bf16_f32 v187, v213, v215
	ds_read_b64_tr_b16 v[188:189], v145 offset:40960
	ds_read_b64_tr_b16 v[190:191], v145 offset:43008
	s_waitcnt lgkmcnt(4)
	v_mfma_f32_16x16x32_bf16 v[164:167], v[176:179], v[172:175], v[164:167]
	ds_read_b64_tr_b16 v[176:177], v144 offset:40960
	ds_read_b64_tr_b16 v[178:179], v144 offset:43008
	v_pk_mul_f32 v[88:89], v[88:89], v[196:197] op_sel_hi:[1,0]
	v_pk_mul_f32 v[86:87], v[86:87], v[196:197] op_sel_hi:[1,0]
	s_waitcnt lgkmcnt(4)
	v_mfma_f32_16x16x32_bf16 v[168:171], v[180:183], v[172:175], v[168:171]
	ds_read_b64_tr_b16 v[172:173], v143 offset:40960
	ds_read_b64_tr_b16 v[174:175], v143 offset:43008
	ds_read_b64_tr_b16 v[180:181], v142 offset:40960
	ds_read_b64_tr_b16 v[182:183], v142 offset:43008
	v_pk_mul_f32 v[96:97], v[96:97], v[196:197] op_sel_hi:[1,0]
	v_pk_mul_f32 v[94:95], v[94:95], v[196:197] op_sel_hi:[1,0]
	s_waitcnt lgkmcnt(0)
	v_mfma_f32_16x16x32_bf16 v[86:89], v[180:183], v[184:187], v[86:89]
	v_add_f32_e32 v180, v200, v201
	v_add_f32_e32 v199, v180, v199
	ds_read_b128 v[180:183], v154 offset:18432
	v_mfma_f32_16x16x32_bf16 v[94:97], v[176:179], v[184:187], v[94:97]
	ds_read_b128 v[176:179], v154 offset:16384
	v_pk_mul_f32 v[100:101], v[100:101], v[196:197] op_sel_hi:[1,0]
	v_pk_mul_f32 v[98:99], v[98:99], v[196:197] op_sel_hi:[1,0]
	v_pk_mul_f32 v[92:93], v[92:93], v[196:197] op_sel_hi:[1,0]
	v_pk_mul_f32 v[90:91], v[90:91], v[196:197] op_sel_hi:[1,0]
	v_mfma_f32_16x16x32_bf16 v[98:101], v[188:191], v[184:187], v[98:101]
	v_add_f32_e32 v188, v203, v205
	v_add_f32_e32 v189, v206, v208
	v_add_f32_e32 v200, v188, v189
	v_mfma_f32_16x16x32_bf16 v[90:93], v[172:175], v[184:187], v[90:93]
	ds_read_b128 v[172:175], v155 offset:16384
	ds_read_b128 v[184:187], v155 offset:18432
	v_fmac_f32_e32 v200, v197, v192
	s_waitcnt lgkmcnt(3)
	v_mfma_f32_16x16x32_bf16 v[180:183], v[180:183], v[82:85], 0
	v_add_f32_e32 v192, v204, v194
	v_add_f32_e32 v194, v207, v209
	ds_read_b128 v[188:191], v155 offset:49152
	s_waitcnt lgkmcnt(3)
	v_mfma_f32_16x16x32_bf16 v[176:179], v[176:179], v[82:85], 0
	v_add_f32_e32 v198, v198, v193
	s_waitcnt lgkmcnt(1)
; __device__ __forceinline__ void attn_b_unit(LAS unsigned char* lds, const bf16* Z, bf16* Y, int unit) {
;     ...
;     for (int st = 0; st < 4; ++st) {
;         const int offA = st * 8192, offB = offA + 4 * 8192;
;         f32x4 SA0, SA1, SB0, SB1;
;         qk_at(kp0, kp1, offA, qf0, qf1, SA0, SA1);
;         qk_at(kp0, kp1, offB, qf0, qf1, SB0, SB1);
; #pragma unroll
;         for (int r = 0; r < 4; ++r) {
;             SA0[r] += tpa[r][st * 32]; SA1[r] += tpb[r][st * 32]; SB0[r] += tpa[r][st * 32 + 128]; SB1[r] += tpb[r][st * 32 + 128];
;         }
;         softmax_step(SA0, SA1, m0, l0, O0);
;         softmax_step(SB0, SB1, m1, l1, O1);
;         pv_at(vp, offA, SA0, SA1, O0);
;         pv_at(vp, offB, SB0, SB1, O1);
;     }
	v_mfma_f32_16x16x32_bf16 v[180:183], v[184:187], v[78:81], v[180:183]
	v_add_f32_e32 v184, v192, v194
	v_add_f32_e32 v197, v184, v200
	ds_read_b128 v[184:187], v154 offset:51200
	v_mfma_f32_16x16x32_bf16 v[172:175], v[172:175], v[78:81], v[176:179]
	v_add_f32_e32 v200, v195, v214
	ds_read_b128 v[192:195], v155 offset:51200
	v_add_f32_e32 v198, v198, v200
	ds_read_b128 v[176:179], v154 offset:49152
	s_waitcnt lgkmcnt(0)
	v_mfma_f32_16x16x32_bf16 v[176:179], v[176:179], v[82:85], 0
	v_fmac_f32_e32 v198, v199, v196
	v_add_f32_e32 v196, v211, v212
	v_add_f32_e32 v199, v213, v215
	v_mfma_f32_16x16x32_bf16 v[184:187], v[184:187], v[82:85], 0
	v_add_f32_e32 v199, v196, v199
	v_add_f32_e32 v198, v199, v198
	v_mfma_f32_16x16x32_bf16 v[176:179], v[188:191], v[78:81], v[176:179]
	ds_read2st64_b32 v[188:189], v153 offset0:1 offset1:3
	ds_read2st64_b32 v[190:191], v152 offset0:1 offset1:3
	s_waitcnt lgkmcnt(1)
	v_add_f32_e32 v188, v172, v188
	v_mfma_f32_16x16x32_bf16 v[184:187], v[192:195], v[78:81], v[184:187]
	ds_read2st64_b32 v[192:193], v151 offset0:1 offset1:3
	ds_read2st64_b32 v[194:195], v149 offset0:1 offset1:3
	s_waitcnt lgkmcnt(2)
	v_add_f32_e32 v190, v180, v190
	v_add_f32_e32 v189, v176, v189
	s_waitcnt lgkmcnt(1)
	v_add_f32_e32 v192, v173, v192
	s_nop 0
	v_add_f32_e32 v191, v184, v191
	ds_read2st64_b32 v[172:173], v147 offset0:1 offset1:3
	s_waitcnt lgkmcnt(1)
	v_add_f32_e32 v194, v181, v194
	v_add_f32_e32 v193, v177, v193
	ds_read2st64_b32 v[176:177], v148 offset0:1 offset1:3
	v_add_f32_e32 v195, v185, v195
	ds_read2st64_b32 v[180:181], v146 offset0:1 offset1:3
	ds_read2st64_b32 v[184:185], v150 offset0:1 offset1:3
	s_waitcnt lgkmcnt(3)
	v_add_f32_e32 v172, v174, v172
	v_add_f32_e32 v173, v178, v173
	s_waitcnt lgkmcnt(2)
	v_add_f32_e32 v174, v182, v176
	s_waitcnt lgkmcnt(1)
	v_add_f32_e32 v175, v175, v180
	s_waitcnt lgkmcnt(0)
	v_add_f32_e32 v176, v183, v184
	v_add_f32_e32 v184, v179, v181
	v_max_f32_e32 v179, v174, v176
	v_add_f32_e32 v182, v186, v177
	v_max_f32_e32 v177, v188, v192
	v_max_f32_e32 v178, v172, v175
	v_max3_f32 v179, v190, v194, v179
	v_max3_f32 v177, v177, v178, v179
	v_mov_b32_e32 v178, v177
	s_nop 1
	v_permlane16_swap_b32_e32 v177, v178
	v_max_f32_e32 v178, v178, v178
	v_max_f32_e32 v177, v177, v177
	v_max_f32_e32 v177, v177, v178
	v_mov_b32_e32 v178, v177
	s_nop 1
	v_permlane32_swap_b32_e32 v177, v178
	v_max3_f32 v200, v202, v177, v178
	v_sub_f32_e32 v172, v172, v200
	v_exp_f32_e32 v204, v172
	v_sub_f32_e32 v172, v174, v200
	v_add_f32_e32 v185, v187, v185
	v_exp_f32_e32 v205, v172
	v_sub_f32_e32 v172, v175, v200
	v_exp_f32_e32 v206, v172
	v_sub_f32_e32 v172, v176, v200
	v_max_f32_e32 v175, v182, v185
	v_exp_f32_e32 v207, v172
	v_max_f32_e32 v172, v189, v193
	v_max_f32_e32 v174, v173, v184
	v_max3_f32 v175, v191, v195, v175
	v_max3_f32 v172, v172, v174, v175
	v_mov_b32_e32 v174, v172
	s_nop 1
	v_permlane16_swap_b32_e32 v172, v174
	v_max_f32_e32 v174, v174, v174
	v_max_f32_e32 v172, v172, v172
	v_max_f32_e32 v172, v172, v174
	v_sub_f32_e32 v178, v188, v200
	v_mov_b32_e32 v174, v172
	v_sub_f32_e32 v177, v202, v200
	v_exp_f32_e32 v201, v178
	v_sub_f32_e32 v178, v190, v200
	v_permlane32_swap_b32_e32 v172, v174
	v_exp_f32_e32 v202, v178
	v_sub_f32_e32 v178, v192, v200
	v_exp_f32_e32 v192, v177
	v_max3_f32 v208, v210, v172, v174
	v_sub_f32_e32 v172, v189, v208
	v_exp_f32_e32 v209, v172
	v_sub_f32_e32 v172, v191, v208
	v_sub_f32_e32 v186, v210, v208
	v_exp_f32_e32 v210, v172
	v_sub_f32_e32 v172, v193, v208
	v_exp_f32_e32 v203, v178
	v_sub_f32_e32 v178, v194, v200
	v_pk_mul_f32 v[158:159], v[158:159], v[192:193] op_sel_hi:[1,0]
	v_pk_mul_f32 v[156:157], v[156:157], v[192:193] op_sel_hi:[1,0]
	v_pk_mul_f32 v[162:163], v[162:163], v[192:193] op_sel_hi:[1,0]
	v_pk_mul_f32 v[160:161], v[160:161], v[192:193] op_sel_hi:[1,0]
	v_pk_mul_f32 v[166:167], v[166:167], v[192:193] op_sel_hi:[1,0]
	v_pk_mul_f32 v[164:165], v[164:165], v[192:193] op_sel_hi:[1,0]
	v_pk_mul_f32 v[170:171], v[170:171], v[192:193] op_sel_hi:[1,0]
	v_pk_mul_f32 v[168:169], v[168:169], v[192:193] op_sel_hi:[1,0]
	v_exp_f32_e32 v193, v172
	v_sub_f32_e32 v172, v195, v208
	v_exp_f32_e32 v194, v178
	v_exp_f32_e32 v211, v172
	v_sub_f32_e32 v180, v173, v208
	v_cvt_pk_bf16_f32 v172, v201, v203
	v_cvt_pk_bf16_f32 v173, v204, v206
	v_cvt_pk_bf16_f32 v174, v202, v194
	v_cvt_pk_bf16_f32 v175, v205, v207
	ds_read_b64_tr_b16 v[176:177], v145 offset:16384
	ds_read_b64_tr_b16 v[178:179], v145 offset:18432
	v_exp_f32_e32 v195, v180
	v_sub_f32_e32 v187, v182, v208
	ds_read_b64_tr_b16 v[180:181], v144 offset:16384
	ds_read_b64_tr_b16 v[182:183], v144 offset:18432
	s_waitcnt lgkmcnt(2)
	v_mfma_f32_16x16x32_bf16 v[156:159], v[176:179], v[172:175], v[156:159]
	v_sub_f32_e32 v176, v185, v208
	v_exp_f32_e32 v214, v176
	v_sub_f32_e32 v184, v184, v208
	s_waitcnt lgkmcnt(0)
	v_mfma_f32_16x16x32_bf16 v[160:163], v[180:183], v[172:175], v[160:163]
	ds_read_b64_tr_b16 v[176:177], v143 offset:16384
	ds_read_b64_tr_b16 v[178:179], v143 offset:18432
	ds_read_b64_tr_b16 v[180:181], v142 offset:16384
	ds_read_b64_tr_b16 v[182:183], v142 offset:18432
	v_exp_f32_e32 v212, v187
	v_exp_f32_e32 v213, v184
	v_exp_f32_e32 v196, v186
	v_cvt_pk_bf16_f32 v184, v209, v193
	v_cvt_pk_bf16_f32 v185, v195, v213
	v_cvt_pk_bf16_f32 v186, v210, v211
	v_cvt_pk_bf16_f32 v187, v212, v214
	ds_read_b64_tr_b16 v[188:189], v145 offset:49152
	ds_read_b64_tr_b16 v[190:191], v145 offset:51200
	s_waitcnt lgkmcnt(4)
	v_mfma_f32_16x16x32_bf16 v[164:167], v[176:179], v[172:175], v[164:167]
	ds_read_b64_tr_b16 v[176:177], v144 offset:49152
	ds_read_b64_tr_b16 v[178:179], v144 offset:51200
	v_pk_mul_f32 v[96:97], v[96:97], v[196:197] op_sel_hi:[1,0]
	v_pk_mul_f32 v[94:95], v[94:95], v[196:197] op_sel_hi:[1,0]
	s_waitcnt lgkmcnt(4)
; __device__ __forceinline__ void attn_b_unit(LAS unsigned char* lds, const bf16* Z, bf16* Y, int unit) {
;     ...
;     for (int st = 0; st < 4; ++st) {
;         const int offA = st * 8192, offB = offA + 4 * 8192;
;         f32x4 SA0, SA1, SB0, SB1;
;         qk_at(kp0, kp1, offA, qf0, qf1, SA0, SA1);
;         qk_at(kp0, kp1, offB, qf0, qf1, SB0, SB1);
; #pragma unroll
;         for (int r = 0; r < 4; ++r) {
;             SA0[r] += tpa[r][st * 32]; SA1[r] += tpb[r][st * 32]; SB0[r] += tpa[r][st * 32 + 128]; SB1[r] += tpb[r][st * 32 + 128];
;         }
;         softmax_step(SA0, SA1, m0, l0, O0);
;         softmax_step(SB0, SB1, m1, l1, O1);
;         pv_at(vp, offA, SA0, SA1, O0);
;         pv_at(vp, offB, SB0, SB1, O1);
;     }
	v_mfma_f32_16x16x32_bf16 v[168:171], v[180:183], v[172:175], v[168:171]
	ds_read_b64_tr_b16 v[172:173], v143 offset:49152
	ds_read_b64_tr_b16 v[174:175], v143 offset:51200
	ds_read_b64_tr_b16 v[180:181], v142 offset:49152
	ds_read_b64_tr_b16 v[182:183], v142 offset:51200
	v_pk_mul_f32 v[88:89], v[88:89], v[196:197] op_sel_hi:[1,0]
	v_pk_mul_f32 v[86:87], v[86:87], v[196:197] op_sel_hi:[1,0]
	s_waitcnt lgkmcnt(4)
	v_mfma_f32_16x16x32_bf16 v[94:97], v[176:179], v[184:187], v[94:97]
	ds_read_b128 v[176:179], v154 offset:24576
	v_pk_mul_f32 v[100:101], v[100:101], v[196:197] op_sel_hi:[1,0]
	v_pk_mul_f32 v[98:99], v[98:99], v[196:197] op_sel_hi:[1,0]
	s_waitcnt lgkmcnt(1)
	v_mfma_f32_16x16x32_bf16 v[86:89], v[180:183], v[184:187], v[86:89]
	ds_read_b128 v[180:183], v154 offset:26624
	v_pk_mul_f32 v[92:93], v[92:93], v[196:197] op_sel_hi:[1,0]
	v_pk_mul_f32 v[90:91], v[90:91], v[196:197] op_sel_hi:[1,0]
	v_mfma_f32_16x16x32_bf16 v[98:101], v[188:191], v[184:187], v[98:101]
	v_add_f32_e32 v188, v202, v194
	v_add_f32_e32 v189, v205, v207
	v_mfma_f32_16x16x32_bf16 v[90:93], v[172:175], v[184:187], v[90:93]
	v_add_f32_e32 v184, v201, v203
	v_add_f32_e32 v185, v204, v206
	ds_read_b128 v[172:175], v155 offset:24576
	v_add_f32_e32 v199, v184, v185
	ds_read_b128 v[184:187], v155 offset:26624
	s_waitcnt lgkmcnt(3)
	v_mfma_f32_16x16x32_bf16 v[176:179], v[176:179], v[82:85], 0
	v_fmac_f32_e32 v199, v197, v192
	v_add_f32_e32 v192, v188, v189
	v_add_f32_e32 v197, v192, v199
	s_waitcnt lgkmcnt(2)
	v_mfma_f32_16x16x32_bf16 v[180:183], v[180:183], v[82:85], 0
	v_add_f32_e32 v192, v209, v193
	ds_read_b128 v[188:191], v155 offset:57344
	s_waitcnt lgkmcnt(2)
	v_mfma_f32_16x16x32_bf16 v[172:175], v[172:175], v[78:81], v[176:179]
	s_nop 2
	ds_read_b128 v[176:179], v154 offset:57344
	s_waitcnt lgkmcnt(2)
	v_mfma_f32_16x16x32_bf16 v[180:183], v[184:187], v[78:81], v[180:183]
	ds_read_b128 v[184:187], v154 offset:59392
	v_add_f32_e32 v154, v195, v213
	v_add_f32_e32 v199, v192, v154
	ds_read_b128 v[192:195], v155 offset:59392
	s_waitcnt lgkmcnt(2)
	v_mfma_f32_16x16x32_bf16 v[176:179], v[176:179], v[82:85], 0
	ds_read2_b32 v[154:155], v153 offset0:96 offset1:224
	ds_read2_b32 v[152:153], v152 offset0:96 offset1:224
	v_fmac_f32_e32 v199, v198, v196
	s_waitcnt lgkmcnt(3)
	v_mfma_f32_16x16x32_bf16 v[82:85], v[184:187], v[82:85], 0
	s_waitcnt lgkmcnt(1)
	v_add_f32_e32 v154, v172, v154
	v_mfma_f32_16x16x32_bf16 v[176:179], v[188:191], v[78:81], v[176:179]
	v_add_f32_e32 v188, v210, v211
	v_add_f32_e32 v189, v212, v214
	v_add_f32_e32 v184, v188, v189
	v_mfma_f32_16x16x32_bf16 v[78:81], v[192:195], v[78:81], v[82:85]
	v_add_f32_e32 v184, v184, v199
	s_nop 2
	v_add_f32_e32 v155, v176, v155
	ds_read2_b32 v[82:83], v151 offset0:96 offset1:224
	ds_read2_b32 v[84:85], v149 offset0:96 offset1:224
	s_waitcnt lgkmcnt(2)
	v_add_f32_e32 v151, v180, v152
	v_add_f32_e32 v176, v78, v153
	ds_read2_b32 v[152:153], v147 offset0:96 offset1:224
	s_waitcnt lgkmcnt(2)
	v_add_f32_e32 v149, v173, v82
	s_waitcnt lgkmcnt(1)
	v_add_f32_e32 v147, v181, v84
	v_add_f32_e32 v173, v177, v83
	ds_read2_b32 v[82:83], v148 offset0:96 offset1:224
	v_add_f32_e32 v177, v79, v85
	ds_read2_b32 v[78:79], v146 offset0:96 offset1:224
	ds_read2_b32 v[84:85], v150 offset0:96 offset1:224
	s_waitcnt lgkmcnt(3)
	v_add_f32_e32 v148, v174, v152
	v_add_f32_e32 v174, v178, v153
	s_waitcnt lgkmcnt(2)
	v_add_f32_e32 v82, v182, v82
	v_add_f32_e32 v178, v80, v83
	s_waitcnt lgkmcnt(0)
	v_add_f32_e32 v80, v183, v84
	v_add_f32_e32 v78, v175, v78
	v_max_f32_e32 v83, v82, v80
	v_add_f32_e32 v175, v179, v79
	v_add_f32_e32 v179, v81, v85
	v_max_f32_e32 v79, v154, v149
	v_max_f32_e32 v81, v148, v78
	v_max3_f32 v83, v151, v147, v83
	v_max3_f32 v79, v79, v81, v83
	v_mov_b32_e32 v81, v79
	s_nop 1
	v_permlane16_swap_b32_e32 v79, v81
	v_max_f32_e32 v81, v81, v81
	v_max_f32_e32 v79, v79, v79
	v_max_f32_e32 v79, v79, v81
	v_mov_b32_e32 v81, v79
	s_nop 1
	v_permlane32_swap_b32_e32 v79, v81
	v_max3_f32 v180, v200, v79, v81
	v_sub_f32_e32 v81, v154, v180
	v_exp_f32_e32 v154, v81
	v_sub_f32_e32 v81, v151, v180
	v_exp_f32_e32 v181, v81
	v_sub_f32_e32 v81, v149, v180
	v_exp_f32_e32 v182, v81
	v_sub_f32_e32 v81, v147, v180
	v_exp_f32_e32 v183, v81
	v_sub_f32_e32 v81, v148, v180
	v_sub_f32_e32 v78, v78, v180
	v_sub_f32_e32 v79, v200, v180
	v_exp_f32_e32 v185, v81
	v_sub_f32_e32 v81, v82, v180
	v_exp_f32_e32 v187, v78
	v_sub_f32_e32 v78, v80, v180
	v_exp_f32_e32 v186, v81
	v_exp_f32_e32 v188, v78
	v_exp_f32_e32 v172, v79
	v_add_f32_e32 v78, v154, v182
	v_add_f32_e32 v79, v185, v187
	v_add_f32_e32 v189, v78, v79
	v_add_f32_e32 v78, v181, v183
	v_add_f32_e32 v79, v186, v188
	v_pk_mul_f32 v[80:81], v[158:159], v[172:173] op_sel_hi:[1,0]
	v_max_f32_e32 v158, v178, v179
	v_add_f32_e32 v190, v78, v79
	v_pk_mul_f32 v[78:79], v[156:157], v[172:173] op_sel_hi:[1,0]
	v_max_f32_e32 v156, v155, v173
	v_max_f32_e32 v157, v174, v175
	v_max3_f32 v158, v176, v177, v158
	v_max3_f32 v156, v156, v157, v158
	v_mov_b32_e32 v157, v156
	s_nop 1
	v_permlane16_swap_b32_e32 v156, v157
	v_max_f32_e32 v157, v157, v157
	v_max_f32_e32 v156, v156, v156
	v_max_f32_e32 v156, v156, v157
	v_mov_b32_e32 v157, v156
	s_nop 1
	v_permlane32_swap_b32_e32 v156, v157
	v_pk_mul_f32 v[152:153], v[170:171], v[172:173] op_sel_hi:[1,0]
	v_max3_f32 v171, v208, v156, v157
	v_sub_f32_e32 v155, v155, v171
	v_exp_f32_e32 v191, v155
	v_sub_f32_e32 v155, v176, v171
	v_exp_f32_e32 v176, v155
	v_sub_f32_e32 v155, v173, v171
	v_pk_mul_f32 v[84:85], v[162:163], v[172:173] op_sel_hi:[1,0]
	v_pk_mul_f32 v[82:83], v[160:161], v[172:173] op_sel_hi:[1,0]
	v_pk_mul_f32 v[148:149], v[166:167], v[172:173] op_sel_hi:[1,0]
	v_pk_mul_f32 v[146:147], v[164:165], v[172:173] op_sel_hi:[1,0]
	v_pk_mul_f32 v[150:151], v[168:169], v[172:173] op_sel_hi:[1,0]
	v_exp_f32_e32 v173, v155
	v_sub_f32_e32 v155, v177, v171
	v_exp_f32_e32 v177, v155
	v_sub_f32_e32 v155, v174, v171
	v_exp_f32_e32 v174, v155
	v_sub_f32_e32 v155, v178, v171
	v_exp_f32_e32 v178, v155
	v_sub_f32_e32 v162, v175, v171
	v_cvt_pk_bf16_f32 v154, v154, v182
	v_cvt_pk_bf16_f32 v155, v185, v187
	v_cvt_pk_bf16_f32 v156, v181, v183
	v_cvt_pk_bf16_f32 v157, v186, v188
	ds_read_b64_tr_b16 v[158:159], v145 offset:24576
	ds_read_b64_tr_b16 v[160:161], v145 offset:26624
	v_exp_f32_e32 v175, v162
	v_sub_f32_e32 v166, v208, v171
	v_sub_f32_e32 v167, v179, v171
	s_waitcnt lgkmcnt(0)
; __device__ __forceinline__ unsigned pk2(float lo, float hi) { return pg8::cvt_pk_bf16(lo, hi); }
; __device__ __forceinline__ size_t tmo(int row, int ct, int nct) { return ((size_t)(row >> 8) * nct + ct) * 32768 + (size_t)(row & 255) * 128; }
; __device__ __forceinline__ void store_o(bf16* yrow, int g, float l, const f32x4 (&O)[4]) {
;     const float inv = 1.0f / xrow16_sum(l);
;     unsigned wx[4], wy[4];
; #pragma unroll
;     for (int db = 0; db < 4; ++db) { wx[db] = pk2(O[db][0] * inv, O[db][1] * inv); wy[db] = pk2(O[db][2] * inv, O[db][3] * inv); }
; #pragma unroll
;     for (int p = 0; p < 2; ++p) {
;         auto rx = __builtin_amdgcn_permlane16_swap(wx[2 * p], wx[2 * p + 1], false, false); wx[2 * p] = rx[0]; wx[2 * p + 1] = rx[1];
;         auto ry = __builtin_amdgcn_permlane16_swap(wy[2 * p], wy[2 * p + 1], false, false); wy[2 * p] = ry[0]; wy[2 * p + 1] = ry[1]; }
; #pragma unroll
;     for (int p = 0; p < 2; ++p) {
;         auto rx = __builtin_amdgcn_permlane32_swap(wx[p], wx[p + 2], false, false); wx[p] = rx[0]; wx[p + 2] = rx[1];
;         auto ry = __builtin_amdgcn_permlane32_swap(wy[p], wy[p + 2], false, false); wy[p] = ry[0]; wy[p + 2] = ry[1]; }
;     v4u lo = {wx[0], wy[0], wx[1], wy[1]}, hi = {wx[2], wy[2], wx[3], wy[3]};
;     *(v4u*)(yrow + 16 * g) = lo; *(v4u*)(yrow + 16 * g + 8) = hi;
; }
; __device__ __forceinline__ void attn_b_unit(LAS unsigned char* lds, const bf16* Z, bf16* Y, int unit) {
;     ...
;     { const float mm = fmaxf(m0, m1), a0 = __builtin_amdgcn_exp2f(m0 - mm), a1 = __builtin_amdgcn_exp2f(m1 - mm);
;       l0 = l0 * a0 + l1 * a1;
; #pragma unroll
;       for (int d = 0; d < 4; ++d) O0[d] = O0[d] * a0 + O1[d] * a1; }
;     store_o((bf16*)((unsigned char*)Y + tmo((int)qtok, 8 + h, 16)), g, l0, O0);
	v_mfma_f32_16x16x32_bf16 v[78:81], v[158:161], v[154:157], v[78:81]
	v_add_f32_e32 v158, v191, v173
	v_add_f32_e32 v159, v174, v175
	ds_read_b64_tr_b16 v[162:163], v144 offset:24576
	ds_read_b64_tr_b16 v[164:165], v144 offset:26624
	v_exp_f32_e32 v179, v167
	v_exp_f32_e32 v170, v166
	ds_read_b64_tr_b16 v[166:167], v143 offset:24576
	ds_read_b64_tr_b16 v[168:169], v143 offset:26624
	v_add_f32_e32 v181, v158, v159
	ds_read_b64_tr_b16 v[158:159], v142 offset:24576
	ds_read_b64_tr_b16 v[160:161], v142 offset:26624
	s_waitcnt lgkmcnt(4)
	v_mfma_f32_16x16x32_bf16 v[82:85], v[162:165], v[154:157], v[82:85]
	v_cvt_pk_bf16_f32 v162, v191, v173
	v_cvt_pk_bf16_f32 v163, v174, v175
	v_cvt_pk_bf16_f32 v164, v176, v177
	s_waitcnt lgkmcnt(2)
	v_mfma_f32_16x16x32_bf16 v[146:149], v[166:169], v[154:157], v[146:149]
	v_cvt_pk_bf16_f32 v165, v178, v179
	ds_read_b64_tr_b16 v[166:167], v145 offset:57344
	ds_read_b64_tr_b16 v[168:169], v145 offset:59392
	v_pk_mul_f32 v[96:97], v[96:97], v[170:171] op_sel_hi:[1,0]
	s_waitcnt lgkmcnt(2)
	v_mfma_f32_16x16x32_bf16 v[150:153], v[158:161], v[154:157], v[150:153]
	ds_read_b64_tr_b16 v[154:155], v144 offset:57344
	ds_read_b64_tr_b16 v[156:157], v144 offset:59392
	ds_read_b64_tr_b16 v[158:159], v143 offset:57344
	ds_read_b64_tr_b16 v[160:161], v143 offset:59392
	v_pk_mul_f32 v[94:95], v[94:95], v[170:171] op_sel_hi:[1,0]
	v_max_f32_e32 v143, v180, v171
	v_add_f32_e32 v182, v176, v177
	s_waitcnt lgkmcnt(2)
	v_mfma_f32_16x16x32_bf16 v[94:97], v[154:157], v[162:165], v[94:97]
	ds_read_b64_tr_b16 v[154:155], v142 offset:57344
	ds_read_b64_tr_b16 v[156:157], v142 offset:59392
	v_sub_f32_e32 v142, v171, v143
	v_exp_f32_e32 v142, v142
	v_sub_f32_e32 v143, v180, v143
	v_exp_f32_e32 v144, v143
	v_add_f32_e32 v145, v178, v179
	v_add_f32_e32 v145, v182, v145
	v_pk_mul_f32 v[94:95], v[142:143], v[94:95] op_sel_hi:[0,1]
	v_fmac_f32_e32 v181, v184, v170
	v_pk_fma_f32 v[82:83], v[144:145], v[82:83], v[94:95] op_sel_hi:[0,1,1]
	v_fmac_f32_e32 v189, v197, v172
	v_add_f32_e32 v95, v145, v181
	v_add_f32_e32 v94, v190, v189
	v_mul_f32_e32 v95, v142, v95
	v_fmac_f32_e32 v95, v144, v94
	v_mov_b32_e32 v94, v95
	s_nop 1
	v_permlane16_swap_b32_e32 v95, v94
	v_add_f32_e32 v94, v95, v94
	v_mov_b32_e32 v95, v94
	s_nop 1
	v_permlane32_swap_b32_e32 v94, v95
	v_add_f32_e32 v94, v94, v95
	v_pk_mul_f32 v[96:97], v[142:143], v[96:97] op_sel_hi:[0,1]
	v_div_scale_f32 v95, s[50:51], v94, v94, 1.0
	v_pk_fma_f32 v[84:85], v[144:145], v[84:85], v[96:97] op_sel_hi:[0,1,1]
	v_rcp_f32_e32 v96, v95
	v_pk_mul_f32 v[100:101], v[100:101], v[170:171] op_sel_hi:[1,0]
	v_pk_mul_f32 v[98:99], v[98:99], v[170:171] op_sel_hi:[1,0]
	v_pk_mul_f32 v[92:93], v[92:93], v[170:171] op_sel_hi:[1,0]
	v_fma_f32 v58, -v95, v96, 1.0
	v_mfma_f32_16x16x32_bf16 v[98:101], v[166:169], v[162:165], v[98:101]
	v_fmac_f32_e32 v96, v58, v96
	v_div_scale_f32 v58, vcc, 1.0, v94, 1.0
	v_mul_f32_e32 v97, v58, v96
	v_pk_mul_f32 v[90:91], v[90:91], v[170:171] op_sel_hi:[1,0]
	s_nop 3
	v_pk_mul_f32 v[98:99], v[142:143], v[98:99] op_sel_hi:[0,1]
	v_pk_fma_f32 v[78:79], v[78:79], v[144:145], v[98:99] op_sel_hi:[1,0,1]
	v_fma_f32 v98, -v95, v97, v58
	v_fmac_f32_e32 v97, v98, v96
	v_fma_f32 v58, -v95, v97, v58
	s_waitcnt lgkmcnt(2)
	v_mfma_f32_16x16x32_bf16 v[90:93], v[158:161], v[162:165], v[90:93]
	v_div_fmas_f32 v58, v58, v96, v97
	v_pk_mul_f32 v[88:89], v[88:89], v[170:171] op_sel_hi:[1,0]
	v_pk_mul_f32 v[86:87], v[86:87], v[170:171] op_sel_hi:[1,0]
	v_pk_mul_f32 v[100:101], v[142:143], v[100:101] op_sel_hi:[0,1]
	v_div_fixup_f32 v58, v58, v94, 1.0
	s_waitcnt lgkmcnt(0)
	v_mfma_f32_16x16x32_bf16 v[86:89], v[154:157], v[162:165], v[86:89]
	v_fma_f32 v80, v80, v144, v100
	v_fma_f32 v81, v81, v144, v101
	v_mul_f32_e32 v78, v78, v58
	v_mul_f32_e32 v79, v79, v58
	v_cvt_pk_bf16_f32 v78, v78, v79
	v_mul_f32_e32 v79, v80, v58
	v_mul_f32_e32 v80, v81, v58
	v_pk_mul_f32 v[90:91], v[142:143], v[90:91] op_sel_hi:[0,1]
	v_cvt_pk_bf16_f32 v79, v79, v80
	v_mul_f32_e32 v80, v82, v58
	v_mul_f32_e32 v81, v83, v58
	v_pk_mul_f32 v[92:93], v[142:143], v[92:93] op_sel_hi:[0,1]
	v_pk_fma_f32 v[90:91], v[144:145], v[146:147], v[90:91] op_sel_hi:[0,1,1]
	v_cvt_pk_bf16_f32 v80, v80, v81
	v_mul_f32_e32 v81, v84, v58
	v_mul_f32_e32 v82, v85, v58
	v_pk_fma_f32 v[92:93], v[144:145], v[148:149], v[92:93] op_sel_hi:[0,1,1]
	v_pk_mul_f32 v[86:87], v[142:143], v[86:87] op_sel_hi:[0,1]
	v_cvt_pk_bf16_f32 v81, v81, v82
	v_mul_f32_e32 v82, v90, v58
	v_mul_f32_e32 v83, v91, v58
	v_pk_mul_f32 v[88:89], v[142:143], v[88:89] op_sel_hi:[0,1]
	v_pk_fma_f32 v[86:87], v[144:145], v[150:151], v[86:87] op_sel_hi:[0,1,1]
	v_cvt_pk_bf16_f32 v82, v82, v83
	v_mul_f32_e32 v83, v92, v58
	v_mul_f32_e32 v84, v93, v58
	v_pk_fma_f32 v[88:89], v[144:145], v[152:153], v[88:89] op_sel_hi:[0,1,1]
	v_cvt_pk_bf16_f32 v83, v83, v84
	v_mul_f32_e32 v84, v86, v58
	v_mul_f32_e32 v85, v87, v58
	v_cvt_pk_bf16_f32 v84, v84, v85
	v_mul_f32_e32 v85, v88, v58
	v_mul_f32_e32 v58, v89, v58
	v_cvt_pk_bf16_f32 v85, v85, v58
	v_lshlrev_b32_e32 v58, 1, v104
	v_lshl_add_u64 v[60:61], v[60:61], 0, v[58:59]
	v_lshl_add_u64 v[86:87], v[60:61], 0, s[28:29]
	v_add_co_u32_e32 v60, vcc, 0x40000, v60
	v_permlane16_swap_b32_e32 v78, v80
	v_permlane16_swap_b32_e32 v79, v81
	v_permlane16_swap_b32_e32 v82, v84
	v_permlane16_swap_b32_e32 v83, v85
	v_addc_co_u32_e32 v61, vcc, 0, v61, vcc
	v_permlane32_swap_b32_e32 v78, v82
	v_permlane32_swap_b32_e32 v79, v83
	v_permlane32_swap_b32_e32 v80, v84
	v_permlane32_swap_b32_e32 v81, v85
	s_andn2_b64 vcc, exec, s[44:45]
	global_store_dwordx4 v[60:61], v[78:81], off
	global_store_dwordx4 v[86:87], v[82:85], off offset:16
	s_barrier
	s_cbranch_vccz .LBB0_294
; #define LAS __attribute__((address_space(3)))
; __device__ __forceinline__ size_t tmo(int row, int ct, int nct) { return ((size_t)(row >> 8) * nct + ct) * 32768 + (size_t)(row & 255) * 128; }
; __device__ __forceinline__ void attn_b_commit(LAS unsigned char* lds, const v4u (&kr)[9], const v4u (&vr)[9], const float (&tr)[2]) {
;     const int tid = threadIdx.x; LAS unsigned char* Kl = lds + B_KOFF; LAS unsigned char* Vl = lds + B_VOFF; LAS float* T = (LAS float*)(lds + B_TOFF);
; #pragma unroll
;     for (int k = 0; k < 9; ++k) { const int it = tid + k * NTHREADS; const int row = it >> 3, ch = it & 7;
;         *(LAS v4u*)(Kl + swz(row, ch)) = kr[k]; *(LAS v4u*)(Vl + swz(row, ch)) = vr[k]; }
; #pragma unroll
;     for (int k = 0; k < 2; ++k) { const int it = tid + k * NTHREADS; if (it < B_TSIZE) T[it] = tr[k]; }
; }
; __device__ __forceinline__ void attn_b_unit(LAS unsigned char* lds, const bf16* Z, bf16* Y, int unit) {
;     const int tid = threadIdx.x, lane = tid & 63, wid = tid >> 6, lq = lane & 15, g = lane >> 4;
;     const int rp = unit & 63, h = (unit >> 6) & 7, b = unit >> 9;
;     const size_t tok0 = (size_t)b * SEQ;
;     const int R0 = clampi(2 * rp - 4, 0, 120);
;     LAS unsigned char* Kl = lds + B_KOFF; LAS unsigned char* Vl = lds + B_VOFF; LAS float* T = (LAS float*)(lds + B_TOFF);
;     const int rq = 2 * rp + (wid >> 2), cb = wid & 3, c = 16 * cb + lq;
;     const int r0q = clampi(rq - 4, 0, 120), kc0 = clampi(16 * cb - 8, 0, 32), cs = clampi(c - 8, 0, 48);
;     const size_t qtok = tok0 + (size_t)rq * 64 + c;
;     const unsigned char* qp = (const unsigned char*)Z + tmo((int)qtok, Z_QB / 64 + h, ZLD / 64) + 16 * g;
;     const bf16x8 qf0 = *(const bf16x8*)qp, qf1 = *(const bf16x8*)(qp + 64);
.LBB0_281:
	v_add_u32_e32 v58, s0, v109
	s_waitcnt vmcnt(13)
	ds_write_b128 v123, v[2:5]
	s_waitcnt vmcnt(12)
	ds_write_b128 v124, v[6:9]
	s_waitcnt vmcnt(11)
	ds_write_b128 v125, v[10:13]
	s_waitcnt vmcnt(10)
	ds_write_b128 v126, v[14:17]
	s_waitcnt vmcnt(9)
	ds_write_b128 v123, v[18:21] offset:16384
	s_waitcnt vmcnt(8)
	ds_write_b128 v127, v[22:25]
	s_waitcnt vmcnt(7)
	ds_write_b128 v128, v[26:29]
	s_waitcnt vmcnt(6)
	ds_write_b128 v129, v[30:33]
	s_waitcnt vmcnt(5)
	ds_write_b128 v123, v[34:37] offset:32768
	s_waitcnt vmcnt(4)
	ds_write_b128 v130, v[38:41]
	s_waitcnt vmcnt(3)
	ds_write_b128 v131, v[42:45]
	s_waitcnt vmcnt(2)
	ds_write_b128 v132, v[46:49]
	s_waitcnt vmcnt(1)
	ds_write_b128 v123, v[50:53] offset:49152
	s_waitcnt vmcnt(0)
	ds_write_b128 v133, v[54:57]
	ds_write_b128 v138, v[66:69]
	ds_write_b128 v139, v[62:65]
	ds_write_b128 v140, v[74:77]
	ds_write_b128 v58, v[70:73]
	v_mul_f32_e32 v141, 0x3fb8aa3b, v141
	s_and_saveexec_b64 s[44:45], s[22:23]
	ds_write_b32 v110, v141
	s_or_b64 exec, exec, s[44:45]
	s_and_saveexec_b64 s[44:45], s[4:5]
	ds_write_b32 v111, v108
	s_or_b64 exec, exec, s[44:45]
	s_and_b32 s51, s58, 0x7e
	v_add_u32_e32 v86, s51, v115
	s_and_b32 s26, s59, 0xffffe000
	v_lshlrev_b32_e32 v87, 6, v86
	v_add_u32_e32 v88, s26, v87
	s_bfe_u32 s50, s72, 0x30006
	v_ashrrev_i32_e32 v88, 8, v88
	s_add_i32 s26, s50, 12
	v_mul_hi_i32_i24_e32 v91, 0x44, v88
	v_mul_i32_i24_e32 v90, 0x44, v88
	v_or_b32_e32 v87, v87, v116
	v_lshl_add_u64 v[90:91], v[90:91], 0, s[26:27]
	v_lshlrev_b64 v[90:91], 15, v[90:91]
	v_lshlrev_b32_e32 v87, 7, v87
	v_and_b32_e32 v88, 0x7f80, v87
	v_mov_b32_e32 v89, 0
	v_lshl_add_u64 v[90:91], s[38:39], 0, v[90:91]
	v_lshl_add_u64 v[90:91], v[90:91], 0, v[88:89]
	v_lshl_add_u64 v[90:91], v[90:91], 0, v[104:105]
	global_load_dwordx4 v[82:85], v[90:91], off
	global_load_dwordx4 v[78:81], v[90:91], off offset:64
	s_add_i32 s55, s72, s33
	s_cmpk_gt_i32 s55, 0xfff
	s_cselect_b64 s[44:45], -1, 0
	s_cmpk_lt_i32 s55, 0x1000
	s_mov_b64 s[50:51], -1
	s_waitcnt lgkmcnt(0)
	s_barrier
	s_cbranch_scc1 .LBB0_287
	s_add_i32 s56, s59, s1
	s_add_i32 s57, s58, s3
	s_mov_b64 s[50:51], 0

; __device__ __forceinline__ void attn_b_prefetch(const bf16* Z, const float* rpb, int unit, v4u (&kr)[9], v4u (&vr)[9], float (&tr)[2]) {
;     ...
;     for (int k = 0; k < 2; ++k) { const int it = tid + k * NTHREADS, e = it - 16, dr = e >> 5, dc = e & 31;
;         tr[k] = (it >= B_TREAL) ? -INFINITY : ((e >= 0 && dr < 15 && dc < 31) ? rpb[h * 465 + dr * 31 + dc] * LOG2E : 0.f); }
.LBB0_293:
	s_mulk_i32 s73, 0x1d1
	v_add_u32_e32 v60, s73, v112
	v_ashrrev_i32_e32 v61, 31, v60
	v_lshl_add_u64 v[60:61], v[60:61], 2, s[46:47]
	global_load_dword v141, v[60:61], off
	s_branch .LBB0_279
